# FFN-in epilogue: activation stores with the nontemporal hint (cache-policy lever for streaming outputs)
# speedup vs baseline: 1.0130x; 1.0051x over previous
.LBB0_623:
	v_lshl_or_b32 v161, s10, 7, v147
	v_lshl_add_u32 v159, s12, 8, v3
	s_movk_i32 s9, 0x1600
	v_mul_lo_u32 v160, v159, s9
	v_lshl_add_u32 v160, v161, 1, v160
	s_andn2_b64 vcc, exec, s[38:39]
	s_mov_b32 s23, 0xffff
	s_mov_b32 s19, s69
	s_mov_b64 s[10:11], -1
	v_mul_f32_e32 v162, 0xbfb8aa3b, v128
	v_mul_f32_e32 v163, 0xbfb8aa3b, v129
	v_mul_f32_e32 v164, 0xbfb8aa3b, v130
	v_mul_f32_e32 v165, 0xbfb8aa3b, v131
	v_mul_f32_e32 v166, 0xbfb8aa3b, v120
	v_mul_f32_e32 v167, 0xbfb8aa3b, v121
	v_mul_f32_e32 v168, 0xbfb8aa3b, v122
	v_mul_f32_e32 v169, 0xbfb8aa3b, v123
	v_exp_f32_e32 v162, v162
	v_exp_f32_e32 v163, v163
	v_exp_f32_e32 v164, v164
	v_exp_f32_e32 v165, v165
	v_exp_f32_e32 v166, v166
	v_exp_f32_e32 v167, v167
	v_exp_f32_e32 v168, v168
	v_exp_f32_e32 v169, v169
	v_add_f32_e32 v162, 1.0, v162
	v_add_f32_e32 v163, 1.0, v163
	v_add_f32_e32 v164, 1.0, v164
	v_add_f32_e32 v165, 1.0, v165
	v_add_f32_e32 v166, 1.0, v166
	v_add_f32_e32 v167, 1.0, v167
	v_add_f32_e32 v168, 1.0, v168
	v_add_f32_e32 v169, 1.0, v169
	v_rcp_f32_e32 v162, v162
	v_rcp_f32_e32 v163, v163
	v_rcp_f32_e32 v164, v164
	v_rcp_f32_e32 v165, v165
	v_rcp_f32_e32 v166, v166
	v_rcp_f32_e32 v167, v167
	v_rcp_f32_e32 v168, v168
	v_rcp_f32_e32 v169, v169
	v_mul_f32_e32 v162, v128, v162
	v_mul_f32_e32 v163, v129, v163
	v_mul_f32_e32 v164, v130, v164
	v_mul_f32_e32 v165, v131, v165
	v_mul_f32_e32 v166, v120, v166
	v_mul_f32_e32 v167, v121, v167
	v_mul_f32_e32 v168, v122, v168
	v_mul_f32_e32 v169, v123, v169
	v_mul_f32_e32 v124, v124, v162
	v_mul_f32_e32 v125, v125, v163
	v_mul_f32_e32 v126, v126, v164
	v_mul_f32_e32 v127, v127, v165
	v_mul_f32_e32 v116, v116, v166
	v_mul_f32_e32 v117, v117, v167
	v_mul_f32_e32 v118, v118, v168
	v_mul_f32_e32 v119, v119, v169
	v_cvt_pk_bf16_f32 v124, v124, v125
	v_cvt_pk_bf16_f32 v125, v126, v127
	v_cvt_pk_bf16_f32 v126, v116, v117
	v_cvt_pk_bf16_f32 v127, v118, v119
	global_store_dwordx4 v160, v[124:127], s[4:5] nt
	v_add_u32_e32 v160, 0x16000, v160
	v_mul_f32_e32 v162, 0xbfb8aa3b, v112
	v_mul_f32_e32 v163, 0xbfb8aa3b, v113
	v_mul_f32_e32 v164, 0xbfb8aa3b, v114
	v_mul_f32_e32 v165, 0xbfb8aa3b, v115
	v_mul_f32_e32 v166, 0xbfb8aa3b, v104
	v_mul_f32_e32 v167, 0xbfb8aa3b, v105
	v_mul_f32_e32 v168, 0xbfb8aa3b, v106
	v_mul_f32_e32 v169, 0xbfb8aa3b, v107
	v_exp_f32_e32 v162, v162
	v_exp_f32_e32 v163, v163
	v_exp_f32_e32 v164, v164
	v_exp_f32_e32 v165, v165
	v_exp_f32_e32 v166, v166
	v_exp_f32_e32 v167, v167
	v_exp_f32_e32 v168, v168
	v_exp_f32_e32 v169, v169
	v_add_f32_e32 v162, 1.0, v162
	v_add_f32_e32 v163, 1.0, v163
	v_add_f32_e32 v164, 1.0, v164
	v_add_f32_e32 v165, 1.0, v165
	v_add_f32_e32 v166, 1.0, v166
	v_add_f32_e32 v167, 1.0, v167
	v_add_f32_e32 v168, 1.0, v168
	v_add_f32_e32 v169, 1.0, v169
	v_rcp_f32_e32 v162, v162
	v_rcp_f32_e32 v163, v163
	v_rcp_f32_e32 v164, v164
	v_rcp_f32_e32 v165, v165
	v_rcp_f32_e32 v166, v166
	v_rcp_f32_e32 v167, v167
	v_rcp_f32_e32 v168, v168
	v_rcp_f32_e32 v169, v169
	v_mul_f32_e32 v162, v112, v162
	v_mul_f32_e32 v163, v113, v163
	v_mul_f32_e32 v164, v114, v164
	v_mul_f32_e32 v165, v115, v165
	v_mul_f32_e32 v166, v104, v166
	v_mul_f32_e32 v167, v105, v167
	v_mul_f32_e32 v168, v106, v168
	v_mul_f32_e32 v169, v107, v169
	v_mul_f32_e32 v108, v108, v162
	v_mul_f32_e32 v109, v109, v163
	v_mul_f32_e32 v110, v110, v164
	v_mul_f32_e32 v111, v111, v165
	v_mul_f32_e32 v100, v100, v166
	v_mul_f32_e32 v101, v101, v167
	v_mul_f32_e32 v102, v102, v168
	v_mul_f32_e32 v103, v103, v169
	v_cvt_pk_bf16_f32 v108, v108, v109
	v_cvt_pk_bf16_f32 v109, v110, v111
	v_cvt_pk_bf16_f32 v110, v100, v101
	v_cvt_pk_bf16_f32 v111, v102, v103
	global_store_dwordx4 v160, v[108:111], s[4:5] nt
	v_add_u32_e32 v160, 0x16000, v160
	v_mul_f32_e32 v162, 0xbfb8aa3b, v96
	v_mul_f32_e32 v163, 0xbfb8aa3b, v97
	v_mul_f32_e32 v164, 0xbfb8aa3b, v98
	v_mul_f32_e32 v165, 0xbfb8aa3b, v99
	v_mul_f32_e32 v166, 0xbfb8aa3b, v88
	v_mul_f32_e32 v167, 0xbfb8aa3b, v89
	v_mul_f32_e32 v168, 0xbfb8aa3b, v90
	v_mul_f32_e32 v169, 0xbfb8aa3b, v91
	v_exp_f32_e32 v162, v162
	v_exp_f32_e32 v163, v163
	v_exp_f32_e32 v164, v164
	v_exp_f32_e32 v165, v165
	v_exp_f32_e32 v166, v166
	v_exp_f32_e32 v167, v167
	v_exp_f32_e32 v168, v168
	v_exp_f32_e32 v169, v169
	v_add_f32_e32 v162, 1.0, v162
	v_add_f32_e32 v163, 1.0, v163
	v_add_f32_e32 v164, 1.0, v164
	v_add_f32_e32 v165, 1.0, v165
	v_add_f32_e32 v166, 1.0, v166
	v_add_f32_e32 v167, 1.0, v167
	v_add_f32_e32 v168, 1.0, v168
	v_add_f32_e32 v169, 1.0, v169
	v_rcp_f32_e32 v162, v162
	v_rcp_f32_e32 v163, v163
	v_rcp_f32_e32 v164, v164
	v_rcp_f32_e32 v165, v165
	v_rcp_f32_e32 v166, v166
	v_rcp_f32_e32 v167, v167
	v_rcp_f32_e32 v168, v168
	v_rcp_f32_e32 v169, v169
	v_mul_f32_e32 v162, v96, v162
	v_mul_f32_e32 v163, v97, v163
	v_mul_f32_e32 v164, v98, v164
	v_mul_f32_e32 v165, v99, v165
	v_mul_f32_e32 v166, v88, v166
	v_mul_f32_e32 v167, v89, v167
	v_mul_f32_e32 v168, v90, v168
	v_mul_f32_e32 v169, v91, v169
	v_mul_f32_e32 v92, v92, v162
	v_mul_f32_e32 v93, v93, v163
	v_mul_f32_e32 v94, v94, v164
	v_mul_f32_e32 v95, v95, v165
	v_mul_f32_e32 v84, v84, v166
	v_mul_f32_e32 v85, v85, v167
	v_mul_f32_e32 v86, v86, v168
	v_mul_f32_e32 v87, v87, v169
	v_cvt_pk_bf16_f32 v92, v92, v93
	v_cvt_pk_bf16_f32 v93, v94, v95
	v_cvt_pk_bf16_f32 v94, v84, v85
	v_cvt_pk_bf16_f32 v95, v86, v87
	global_store_dwordx4 v160, v[92:95], s[4:5] nt
	v_add_u32_e32 v160, 0x16000, v160
	v_mul_f32_e32 v162, 0xbfb8aa3b, v80
	v_mul_f32_e32 v163, 0xbfb8aa3b, v81
	v_mul_f32_e32 v164, 0xbfb8aa3b, v82
	v_mul_f32_e32 v165, 0xbfb8aa3b, v83
	v_mul_f32_e32 v166, 0xbfb8aa3b, v72
	v_mul_f32_e32 v167, 0xbfb8aa3b, v73
	v_mul_f32_e32 v168, 0xbfb8aa3b, v74
	v_mul_f32_e32 v169, 0xbfb8aa3b, v75
	v_exp_f32_e32 v162, v162
	v_exp_f32_e32 v163, v163
	v_exp_f32_e32 v164, v164
	v_exp_f32_e32 v165, v165
	v_exp_f32_e32 v166, v166
	v_exp_f32_e32 v167, v167
	v_exp_f32_e32 v168, v168
	v_exp_f32_e32 v169, v169
	v_add_f32_e32 v162, 1.0, v162
	v_add_f32_e32 v163, 1.0, v163
	v_add_f32_e32 v164, 1.0, v164
	v_add_f32_e32 v165, 1.0, v165
	v_add_f32_e32 v166, 1.0, v166
	v_add_f32_e32 v167, 1.0, v167
	v_add_f32_e32 v168, 1.0, v168
	v_add_f32_e32 v169, 1.0, v169
	v_rcp_f32_e32 v162, v162
	v_rcp_f32_e32 v163, v163
	v_rcp_f32_e32 v164, v164
	v_rcp_f32_e32 v165, v165
	v_rcp_f32_e32 v166, v166
	v_rcp_f32_e32 v167, v167
	v_rcp_f32_e32 v168, v168
	v_rcp_f32_e32 v169, v169
	v_mul_f32_e32 v162, v80, v162
	v_mul_f32_e32 v163, v81, v163
	v_mul_f32_e32 v164, v82, v164
	v_mul_f32_e32 v165, v83, v165
	v_mul_f32_e32 v166, v72, v166
	v_mul_f32_e32 v167, v73, v167
	v_mul_f32_e32 v168, v74, v168
	v_mul_f32_e32 v169, v75, v169
	v_mul_f32_e32 v76, v76, v162
	v_mul_f32_e32 v77, v77, v163
	v_mul_f32_e32 v78, v78, v164
	v_mul_f32_e32 v79, v79, v165
	v_mul_f32_e32 v68, v68, v166
	v_mul_f32_e32 v69, v69, v167
	v_mul_f32_e32 v70, v70, v168
	v_mul_f32_e32 v71, v71, v169
	v_cvt_pk_bf16_f32 v76, v76, v77
	v_cvt_pk_bf16_f32 v77, v78, v79
	v_cvt_pk_bf16_f32 v78, v68, v69
	v_cvt_pk_bf16_f32 v79, v70, v71
	global_store_dwordx4 v160, v[76:79], s[4:5] nt
	v_add_u32_e32 v160, 0x6e000, v160
	v_mul_f32_e32 v162, 0xbfb8aa3b, v64
	v_mul_f32_e32 v163, 0xbfb8aa3b, v65
	v_mul_f32_e32 v164, 0xbfb8aa3b, v66
	v_mul_f32_e32 v165, 0xbfb8aa3b, v67
	v_mul_f32_e32 v166, 0xbfb8aa3b, v56
	v_mul_f32_e32 v167, 0xbfb8aa3b, v57
	v_mul_f32_e32 v168, 0xbfb8aa3b, v58
	v_mul_f32_e32 v169, 0xbfb8aa3b, v59
	v_exp_f32_e32 v162, v162
	v_exp_f32_e32 v163, v163
	v_exp_f32_e32 v164, v164
	v_exp_f32_e32 v165, v165
	v_exp_f32_e32 v166, v166
	v_exp_f32_e32 v167, v167
	v_exp_f32_e32 v168, v168
	v_exp_f32_e32 v169, v169
	v_add_f32_e32 v162, 1.0, v162
	v_add_f32_e32 v163, 1.0, v163
	v_add_f32_e32 v164, 1.0, v164
	v_add_f32_e32 v165, 1.0, v165
	v_add_f32_e32 v166, 1.0, v166
	v_add_f32_e32 v167, 1.0, v167
	v_add_f32_e32 v168, 1.0, v168
	v_add_f32_e32 v169, 1.0, v169
	v_rcp_f32_e32 v162, v162
	v_rcp_f32_e32 v163, v163
	v_rcp_f32_e32 v164, v164
	v_rcp_f32_e32 v165, v165
	v_rcp_f32_e32 v166, v166
	v_rcp_f32_e32 v167, v167
	v_rcp_f32_e32 v168, v168
	v_rcp_f32_e32 v169, v169
	v_mul_f32_e32 v162, v64, v162
	v_mul_f32_e32 v163, v65, v163
	v_mul_f32_e32 v164, v66, v164
	v_mul_f32_e32 v165, v67, v165
	v_mul_f32_e32 v166, v56, v166
	v_mul_f32_e32 v167, v57, v167
	v_mul_f32_e32 v168, v58, v168
	v_mul_f32_e32 v169, v59, v169
	v_mul_f32_e32 v60, v60, v162
	v_mul_f32_e32 v61, v61, v163
	v_mul_f32_e32 v62, v62, v164
	v_mul_f32_e32 v63, v63, v165
	v_mul_f32_e32 v52, v52, v166
	v_mul_f32_e32 v53, v53, v167
	v_mul_f32_e32 v54, v54, v168
	v_mul_f32_e32 v55, v55, v169
	v_cvt_pk_bf16_f32 v60, v60, v61
	v_cvt_pk_bf16_f32 v61, v62, v63
	v_cvt_pk_bf16_f32 v62, v52, v53
	v_cvt_pk_bf16_f32 v63, v54, v55
	global_store_dwordx4 v160, v[60:63], s[4:5] nt
	v_add_u32_e32 v160, 0x16000, v160
	v_mul_f32_e32 v162, 0xbfb8aa3b, v48
	v_mul_f32_e32 v163, 0xbfb8aa3b, v49
	v_mul_f32_e32 v164, 0xbfb8aa3b, v50
	v_mul_f32_e32 v165, 0xbfb8aa3b, v51
	v_mul_f32_e32 v166, 0xbfb8aa3b, v40
	v_mul_f32_e32 v167, 0xbfb8aa3b, v41
	v_mul_f32_e32 v168, 0xbfb8aa3b, v42
	v_mul_f32_e32 v169, 0xbfb8aa3b, v43
	v_exp_f32_e32 v162, v162
	v_exp_f32_e32 v163, v163
	v_exp_f32_e32 v164, v164
	v_exp_f32_e32 v165, v165
	v_exp_f32_e32 v166, v166
	v_exp_f32_e32 v167, v167
	v_exp_f32_e32 v168, v168
	v_exp_f32_e32 v169, v169
	v_add_f32_e32 v162, 1.0, v162
	v_add_f32_e32 v163, 1.0, v163
	v_add_f32_e32 v164, 1.0, v164
	v_add_f32_e32 v165, 1.0, v165
	v_add_f32_e32 v166, 1.0, v166
	v_add_f32_e32 v167, 1.0, v167
	v_add_f32_e32 v168, 1.0, v168
	v_add_f32_e32 v169, 1.0, v169
	v_rcp_f32_e32 v162, v162
	v_rcp_f32_e32 v163, v163
	v_rcp_f32_e32 v164, v164
	v_rcp_f32_e32 v165, v165
	v_rcp_f32_e32 v166, v166
	v_rcp_f32_e32 v167, v167
	v_rcp_f32_e32 v168, v168
	v_rcp_f32_e32 v169, v169
	v_mul_f32_e32 v162, v48, v162
	v_mul_f32_e32 v163, v49, v163
	v_mul_f32_e32 v164, v50, v164
	v_mul_f32_e32 v165, v51, v165
	v_mul_f32_e32 v166, v40, v166
	v_mul_f32_e32 v167, v41, v167
	v_mul_f32_e32 v168, v42, v168
	v_mul_f32_e32 v169, v43, v169
	v_mul_f32_e32 v44, v44, v162
	v_mul_f32_e32 v45, v45, v163
	v_mul_f32_e32 v46, v46, v164
	v_mul_f32_e32 v47, v47, v165
	v_mul_f32_e32 v36, v36, v166
	v_mul_f32_e32 v37, v37, v167
	v_mul_f32_e32 v38, v38, v168
	v_mul_f32_e32 v39, v39, v169
	v_cvt_pk_bf16_f32 v44, v44, v45
	v_cvt_pk_bf16_f32 v45, v46, v47
	v_cvt_pk_bf16_f32 v46, v36, v37
	v_cvt_pk_bf16_f32 v47, v38, v39
	global_store_dwordx4 v160, v[44:47], s[4:5] nt
	v_add_u32_e32 v160, 0x16000, v160
	v_mul_f32_e32 v162, 0xbfb8aa3b, v32
	v_mul_f32_e32 v163, 0xbfb8aa3b, v33
	v_mul_f32_e32 v164, 0xbfb8aa3b, v34
	v_mul_f32_e32 v165, 0xbfb8aa3b, v35
	v_mul_f32_e32 v166, 0xbfb8aa3b, v24
	v_mul_f32_e32 v167, 0xbfb8aa3b, v25
	v_mul_f32_e32 v168, 0xbfb8aa3b, v26
	v_mul_f32_e32 v169, 0xbfb8aa3b, v27
	v_exp_f32_e32 v162, v162
	v_exp_f32_e32 v163, v163
	v_exp_f32_e32 v164, v164
	v_exp_f32_e32 v165, v165
	v_exp_f32_e32 v166, v166
	v_exp_f32_e32 v167, v167
	v_exp_f32_e32 v168, v168
	v_exp_f32_e32 v169, v169
	v_add_f32_e32 v162, 1.0, v162
	v_add_f32_e32 v163, 1.0, v163
	v_add_f32_e32 v164, 1.0, v164
	v_add_f32_e32 v165, 1.0, v165
	v_add_f32_e32 v166, 1.0, v166
	v_add_f32_e32 v167, 1.0, v167
	v_add_f32_e32 v168, 1.0, v168
	v_add_f32_e32 v169, 1.0, v169
	v_rcp_f32_e32 v162, v162
	v_rcp_f32_e32 v163, v163
	v_rcp_f32_e32 v164, v164
	v_rcp_f32_e32 v165, v165
	v_rcp_f32_e32 v166, v166
	v_rcp_f32_e32 v167, v167
	v_rcp_f32_e32 v168, v168
	v_rcp_f32_e32 v169, v169
	v_mul_f32_e32 v162, v32, v162
	v_mul_f32_e32 v163, v33, v163
	v_mul_f32_e32 v164, v34, v164
	v_mul_f32_e32 v165, v35, v165
	v_mul_f32_e32 v166, v24, v166
	v_mul_f32_e32 v167, v25, v167
	v_mul_f32_e32 v168, v26, v168
	v_mul_f32_e32 v169, v27, v169
	v_mul_f32_e32 v28, v28, v162
	v_mul_f32_e32 v29, v29, v163
	v_mul_f32_e32 v30, v30, v164
	v_mul_f32_e32 v31, v31, v165
	v_mul_f32_e32 v20, v20, v166
	v_mul_f32_e32 v21, v21, v167
	v_mul_f32_e32 v22, v22, v168
	v_mul_f32_e32 v23, v23, v169
	v_cvt_pk_bf16_f32 v28, v28, v29
	v_cvt_pk_bf16_f32 v29, v30, v31
	v_cvt_pk_bf16_f32 v30, v20, v21
	v_cvt_pk_bf16_f32 v31, v22, v23
	global_store_dwordx4 v160, v[28:31], s[4:5] nt
	v_add_u32_e32 v160, 0x16000, v160
	v_mul_f32_e32 v162, 0xbfb8aa3b, v16
	v_mul_f32_e32 v163, 0xbfb8aa3b, v17
	v_mul_f32_e32 v164, 0xbfb8aa3b, v18
	v_mul_f32_e32 v165, 0xbfb8aa3b, v19
	v_mul_f32_e32 v166, 0xbfb8aa3b, v8
	v_mul_f32_e32 v167, 0xbfb8aa3b, v9
	v_mul_f32_e32 v168, 0xbfb8aa3b, v10
	v_mul_f32_e32 v169, 0xbfb8aa3b, v11
	v_exp_f32_e32 v162, v162
	v_exp_f32_e32 v163, v163
	v_exp_f32_e32 v164, v164
	v_exp_f32_e32 v165, v165
	v_exp_f32_e32 v166, v166
	v_exp_f32_e32 v167, v167
	v_exp_f32_e32 v168, v168
	v_exp_f32_e32 v169, v169
	v_add_f32_e32 v162, 1.0, v162
	v_add_f32_e32 v163, 1.0, v163
	v_add_f32_e32 v164, 1.0, v164
	v_add_f32_e32 v165, 1.0, v165
	v_add_f32_e32 v166, 1.0, v166
	v_add_f32_e32 v167, 1.0, v167
	v_add_f32_e32 v168, 1.0, v168
	v_add_f32_e32 v169, 1.0, v169
	v_rcp_f32_e32 v162, v162
	v_rcp_f32_e32 v163, v163
	v_rcp_f32_e32 v164, v164
	v_rcp_f32_e32 v165, v165
	v_rcp_f32_e32 v166, v166
	v_rcp_f32_e32 v167, v167
	v_rcp_f32_e32 v168, v168
	v_rcp_f32_e32 v169, v169
	v_mul_f32_e32 v162, v16, v162
	v_mul_f32_e32 v163, v17, v163
	v_mul_f32_e32 v164, v18, v164
	v_mul_f32_e32 v165, v19, v165
	v_mul_f32_e32 v166, v8, v166
	v_mul_f32_e32 v167, v9, v167
	v_mul_f32_e32 v168, v10, v168
	v_mul_f32_e32 v169, v11, v169
	v_mul_f32_e32 v12, v12, v162
	v_mul_f32_e32 v13, v13, v163
	v_mul_f32_e32 v14, v14, v164
	v_mul_f32_e32 v15, v15, v165
	v_mul_f32_e32 v4, v4, v166
	v_mul_f32_e32 v5, v5, v167
	v_mul_f32_e32 v6, v6, v168
	v_mul_f32_e32 v7, v7, v169
	v_cvt_pk_bf16_f32 v12, v12, v13
	v_cvt_pk_bf16_f32 v13, v14, v15
	v_cvt_pk_bf16_f32 v14, v4, v5
	v_cvt_pk_bf16_f32 v15, v6, v7
	global_store_dwordx4 v160, v[12:15], s[4:5] nt
	s_cbranch_vccnz .LBB0_613
	s_andn2_b64 vcc, exec, s[0:1]
	s_cbranch_vccnz .LBB0_612
	s_barrier
	s_branch .LBB0_612
